# MoBA new-head path: K-load ladder removed (v_cvt moved behind vmcnt(25)); T5 bias table filled only for the workgroup's first head (same h for both)
# baseline (speedup 1.0000x reference)
; template<int THRL> __device__ __forceinline__ void attn_unit(int b,int h,int qb,const bf16*Q,const bf16*__restrict__ K,const bf16*__restrict__ V,bf16*O,char*shm,const float*KMg,const float*rel_bias,bool newhead,bf16x8 (&qr)[4],const bf16*Qnext){
;     ...
;   if(newhead){
;     {
;       const bf16*Kn=K+(long)(b*NHEAD+h)*SEQ*D+(long)(tid>>3)*D+(tid&7)*8; const lds_fptr kpart=(lds_fptr)(shm+LDS_TOTAL);
;       h16x8v kv_[32];
;       #pragma unroll
;       for(int i=0;i<32;++i)kv_[i]=*reinterpret_cast<const h16x8v*>(Kn+(long)i*64*D);
.LBB0_420:
	s_getreg_b32 s8, hwreg(HW_REG_HW_ID, 0, 6)
	s_and_b32 s8, s8, 63
	s_lshl_b32 s8, s8, 2
	s_or_b32 s8, s8, 0x25000
	v_mov_b32_e32 v1, s8
	ds_read_b32 v1, v1
	s_ashr_i32 s7, s43, 3
	s_and_b32 s6, s43, 0xff
	s_and_b32 s7, s7, 0xffffff00
	s_or_b32 s49, s7, s6
	s_waitcnt lgkmcnt(0)
	v_readfirstlane_b32 s6, v1
	s_and_b32 s76, s43, 15
	v_mbcnt_lo_u32_b32 v2, -1, 0
	v_mbcnt_hi_u32_b32 v2, -1, v2
	s_mov_b64 s[8:9], -1
	v_lshl_add_u32 v17, s6, 6, v2
	s_and_b32 s6, s49, -16
	s_or_b32 s6, s6, s76
	v_readfirstlane_b32 s42, v17
	s_ashr_i32 s77, s42, 6
	s_ashr_i32 s7, s6, 31
	s_cmp_lg_u32 s49, s5
	v_and_b32_e32 v238, 63, v17
	v_lshlrev_b32_e32 v1, 3, v17
	s_cbranch_scc0 .LBB0_445
	s_lshl_b64 s[8:9], s[6:7], 18
	v_readlane_b32 s5, v254, 18
	v_ashrrev_i32_e32 v2, 3, v17
	s_add_u32 s8, s5, s8
	v_readlane_b32 s5, v254, 19
	v_ashrrev_i32_e32 v3, 31, v2
	v_lshlrev_b32_e32 v239, 3, v17
	s_addc_u32 s9, s5, s9
	v_lshlrev_b64 v[2:3], 7, v[2:3]
	v_and_b32_e32 v134, 56, v239
	v_lshl_add_u64 v[2:3], s[8:9], 0, v[2:3]
	v_lshlrev_b32_e32 v4, 1, v134
	v_mov_b32_e32 v5, v0
	s_waitcnt vmcnt(0)
	v_lshl_add_u64 v[14:15], v[2:3], 0, v[4:5]
	s_movk_i32 s5, 0x2000
	v_add_co_u32_e32 v2, vcc, s5, v14
	s_movk_i32 s5, 0x4000
	s_nop 0
	v_addc_co_u32_e32 v3, vcc, 0, v15, vcc
	global_load_dwordx4 v[118:121], v[14:15], off
	global_load_dwordx4 v[126:129], v[2:3], off
	v_add_co_u32_e32 v2, vcc, s5, v14
	s_movk_i32 s5, 0x6000
	s_nop 0
	v_addc_co_u32_e32 v3, vcc, 0, v15, vcc
	global_load_dwordx4 v[122:125], v[2:3], off
	v_add_co_u32_e32 v2, vcc, s5, v14
	s_mov_b32 s5, 0xa000
	s_nop 0
	v_addc_co_u32_e32 v3, vcc, 0, v15, vcc
	global_load_dwordx4 v[130:133], v[2:3], off
	v_add_co_u32_e32 v2, vcc, s78, v14
	v_addc_co_u32_e32 v3, vcc, 0, v15, vcc
	global_load_dwordx4 v[102:105], v[2:3], off
	v_add_co_u32_e32 v2, vcc, s5, v14
	s_mov_b32 s5, 0xc000
	s_nop 0
	v_addc_co_u32_e32 v3, vcc, 0, v15, vcc
	global_load_dwordx4 v[110:113], v[2:3], off
	v_add_co_u32_e32 v2, vcc, s5, v14
	s_mov_b32 s5, 0xe000
	s_nop 0
	v_addc_co_u32_e32 v3, vcc, 0, v15, vcc
	global_load_dwordx4 v[106:109], v[2:3], off
	v_add_co_u32_e32 v2, vcc, s5, v14
	s_mov_b32 s5, 0x10000
	s_nop 0
	v_addc_co_u32_e32 v3, vcc, 0, v15, vcc
	global_load_dwordx4 v[114:117], v[2:3], off
	v_add_co_u32_e32 v2, vcc, s5, v14
	s_mov_b32 s5, 0x12000
	s_nop 0
	v_addc_co_u32_e32 v3, vcc, 0, v15, vcc
	global_load_dwordx4 v[86:89], v[2:3], off
	v_add_co_u32_e32 v2, vcc, s5, v14
	s_mov_b32 s5, 0x14000
	s_nop 0
	v_addc_co_u32_e32 v3, vcc, 0, v15, vcc
	global_load_dwordx4 v[94:97], v[2:3], off
	v_add_co_u32_e32 v2, vcc, s5, v14
	s_mov_b32 s5, 0x16000
	s_nop 0
	v_addc_co_u32_e32 v3, vcc, 0, v15, vcc
	global_load_dwordx4 v[90:93], v[2:3], off
	v_add_co_u32_e32 v2, vcc, s5, v14
	s_mov_b32 s5, 0x18000
	s_nop 0
	v_addc_co_u32_e32 v3, vcc, 0, v15, vcc
	global_load_dwordx4 v[98:101], v[2:3], off
	v_add_co_u32_e32 v2, vcc, s5, v14
	s_mov_b32 s5, 0x1a000
	s_nop 0
	v_addc_co_u32_e32 v3, vcc, 0, v15, vcc
	global_load_dwordx4 v[70:73], v[2:3], off
	v_add_co_u32_e32 v2, vcc, s5, v14
	s_mov_b32 s5, 0x1c000
	s_nop 0
	v_addc_co_u32_e32 v3, vcc, 0, v15, vcc
	global_load_dwordx4 v[78:81], v[2:3], off
	v_add_co_u32_e32 v2, vcc, s5, v14
	s_mov_b32 s5, 0x1e000
	s_nop 0
	v_addc_co_u32_e32 v3, vcc, 0, v15, vcc
	global_load_dwordx4 v[74:77], v[2:3], off
	v_add_co_u32_e32 v2, vcc, s5, v14
	s_mov_b32 s5, 0x20000
	s_nop 0
	v_addc_co_u32_e32 v3, vcc, 0, v15, vcc
	global_load_dwordx4 v[82:85], v[2:3], off
	v_add_co_u32_e32 v2, vcc, s5, v14
	s_mov_b32 s5, 0x22000
	s_nop 0
	v_addc_co_u32_e32 v3, vcc, 0, v15, vcc
	global_load_dwordx4 v[54:57], v[2:3], off
	v_add_co_u32_e32 v2, vcc, s5, v14
	s_mov_b32 s5, 0x24000
	s_nop 0
	v_addc_co_u32_e32 v3, vcc, 0, v15, vcc
	global_load_dwordx4 v[62:65], v[2:3], off
	v_add_co_u32_e32 v2, vcc, s5, v14
	s_mov_b32 s5, 0x26000
	s_nop 0
	v_addc_co_u32_e32 v3, vcc, 0, v15, vcc
	global_load_dwordx4 v[58:61], v[2:3], off
	v_add_co_u32_e32 v2, vcc, s5, v14
	s_mov_b32 s5, 0x28000
	s_nop 0
	v_addc_co_u32_e32 v3, vcc, 0, v15, vcc
	global_load_dwordx4 v[66:69], v[2:3], off
	v_add_co_u32_e32 v2, vcc, s5, v14
	s_mov_b32 s5, 0x2a000
	s_nop 0
	v_addc_co_u32_e32 v3, vcc, 0, v15, vcc
	global_load_dwordx4 v[38:41], v[2:3], off
	v_add_co_u32_e32 v2, vcc, s5, v14
	s_mov_b32 s5, 0x2c000
	s_nop 0
	v_addc_co_u32_e32 v3, vcc, 0, v15, vcc
	global_load_dwordx4 v[46:49], v[2:3], off
	v_add_co_u32_e32 v2, vcc, s5, v14
	s_mov_b32 s5, 0x2e000
	s_nop 0
	v_addc_co_u32_e32 v3, vcc, 0, v15, vcc
	global_load_dwordx4 v[42:45], v[2:3], off
	v_add_co_u32_e32 v2, vcc, s5, v14
	s_mov_b32 s5, 0x30000
	s_nop 0
	v_addc_co_u32_e32 v3, vcc, 0, v15, vcc
	global_load_dwordx4 v[50:53], v[2:3], off
	v_add_co_u32_e32 v2, vcc, s5, v14
	s_mov_b32 s5, 0x32000
	s_nop 0
	v_addc_co_u32_e32 v3, vcc, 0, v15, vcc
	global_load_dwordx4 v[22:25], v[2:3], off
	v_add_co_u32_e32 v2, vcc, s5, v14
	s_mov_b32 s5, 0x34000
	s_nop 0
	v_addc_co_u32_e32 v3, vcc, 0, v15, vcc
	global_load_dwordx4 v[30:33], v[2:3], off
	v_add_co_u32_e32 v2, vcc, s5, v14
	s_mov_b32 s5, 0x36000
	s_nop 0
	v_addc_co_u32_e32 v3, vcc, 0, v15, vcc
	global_load_dwordx4 v[26:29], v[2:3], off
	v_add_co_u32_e32 v2, vcc, s5, v14
	s_mov_b32 s5, 0x38000
	s_nop 0
	v_addc_co_u32_e32 v3, vcc, 0, v15, vcc
	global_load_dwordx4 v[34:37], v[2:3], off
	v_add_co_u32_e32 v2, vcc, s5, v14
	s_mov_b32 s5, 0x3a000
	s_nop 0
	v_addc_co_u32_e32 v3, vcc, 0, v15, vcc
	v_add_co_u32_e32 v6, vcc, s5, v14
	s_mov_b32 s5, 0x3c000
	s_nop 0
	v_addc_co_u32_e32 v7, vcc, 0, v15, vcc
	global_load_dwordx4 v[2:5], v[2:3], off
	s_waitcnt vmcnt(25)
; template<int THRL> __device__ __forceinline__ void attn_unit(int b,int h,int qb,const bf16*Q,const bf16*__restrict__ K,const bf16*__restrict__ V,bf16*O,char*shm,const float*KMg,const float*rel_bias,bool newhead,bf16x8 (&qr)[4],const bf16*Qnext){
;     ...
;       const bf16*Kn=K+(long)(b*NHEAD+h)*SEQ*D+(long)(tid>>3)*D+(tid&7)*8; const lds_fptr kpart=(lds_fptr)(shm+LDS_TOTAL);
;       h16x8v kv_[32];
;       #pragma unroll
;       for(int i=0;i<32;++i)kv_[i]=*reinterpret_cast<const h16x8v*>(Kn+(long)i*64*D);
;       #pragma unroll
;       for(int n=0;n<8;++n){ float a_[8];
;         #pragma unroll
;         for(int e=0;e<8;++e)a_[e]=((float)kv_[4*n][e]+(float)kv_[4*n+1][e])+((float)kv_[4*n+2][e]+(float)kv_[4*n+3][e]);
;         #pragma unroll
;         for(int e=0;e<8;++e){ a_[e]+=__shfl_xor(a_[e],8); a_[e]+=__shfl_xor(a_[e],16); a_[e]+=__shfl_xor(a_[e],32); }
;         if((lane>>3)==0){
;           #pragma unroll
;           for(int e=0;e<8;++e)kpart[(wid*8+n)*64+(lane&7)*8+e]=a_[e]; } }
	v_cvt_f32_f16_sdwa v135, v126 dst_sel:DWORD dst_unused:UNUSED_PAD src0_sel:WORD_1
	v_cvt_f32_f16_e32 v140, v130
	global_load_dwordx4 v[10:13], v[6:7], off
	v_add_co_u32_e32 v6, vcc, s5, v14
	s_mov_b32 s5, 0x3e000
	s_nop 0
	v_addc_co_u32_e32 v7, vcc, 0, v15, vcc
	v_add_co_u32_e32 v14, vcc, s5, v14
	global_load_dwordx4 v[6:9], v[6:7], off
	s_nop 0
	v_addc_co_u32_e32 v15, vcc, 0, v15, vcc
	global_load_dwordx4 v[18:21], v[14:15], off
	v_and_b32_e32 v15, 64, v237
	v_xor_b32_e32 v14, 8, v237
	v_add_u32_e32 v15, 64, v15
	v_cmp_lt_i32_e32 vcc, v14, v15
	s_lshl_b32 s5, s77, 11
	s_add_i32 s5, s5, 0
	v_cndmask_b32_e32 v14, v237, v14, vcc
	v_lshlrev_b32_e32 v139, 2, v14
	v_xor_b32_e32 v14, 16, v237
	v_cmp_lt_i32_e32 vcc, v14, v15
	s_add_i32 s5, s5, 0x1b800
	v_lshl_add_u32 v136, v134, 2, s5
	v_cndmask_b32_e32 v14, v237, v14, vcc
	v_lshlrev_b32_e32 v138, 2, v14
	v_xor_b32_e32 v14, 32, v237
	v_cmp_lt_i32_e32 vcc, v14, v15
	v_cvt_f32_f16_sdwa v15, v118 dst_sel:DWORD dst_unused:UNUSED_PAD src0_sel:WORD_1
	v_cvt_f32_f16_e32 v134, v126
	v_cndmask_b32_e32 v14, v237, v14, vcc
	v_lshlrev_b32_e32 v137, 2, v14
	v_cvt_f32_f16_e32 v14, v118
	v_cvt_f32_f16_e32 v118, v119
	v_cvt_f32_f16_sdwa v119, v119 dst_sel:DWORD dst_unused:UNUSED_PAD src0_sel:WORD_1
	v_cvt_f32_f16_e32 v126, v127
	v_cvt_f32_f16_sdwa v127, v127 dst_sel:DWORD dst_unused:UNUSED_PAD src0_sel:WORD_1
	v_pk_add_f32 v[14:15], v[14:15], v[134:135]
	v_cvt_f32_f16_e32 v134, v122
	v_cvt_f32_f16_sdwa v135, v122 dst_sel:DWORD dst_unused:UNUSED_PAD src0_sel:WORD_1
	v_pk_add_f32 v[118:119], v[118:119], v[126:127]
	v_cvt_f32_f16_e32 v122, v123
	v_cvt_f32_f16_sdwa v123, v123 dst_sel:DWORD dst_unused:UNUSED_PAD src0_sel:WORD_1
	v_cvt_f32_f16_e32 v126, v131
	v_cvt_f32_f16_sdwa v127, v131 dst_sel:DWORD dst_unused:UNUSED_PAD src0_sel:WORD_1
	v_cvt_f32_f16_sdwa v141, v130 dst_sel:DWORD dst_unused:UNUSED_PAD src0_sel:WORD_1
	v_cvt_f32_f16_e32 v130, v128
	v_cvt_f32_f16_sdwa v131, v128 dst_sel:DWORD dst_unused:UNUSED_PAD src0_sel:WORD_1
	v_pk_add_f32 v[122:123], v[122:123], v[126:127]
	v_cvt_f32_f16_e32 v126, v120
	v_cvt_f32_f16_sdwa v127, v120 dst_sel:DWORD dst_unused:UNUSED_PAD src0_sel:WORD_1
	v_cvt_f32_f16_e32 v120, v121
	v_cvt_f32_f16_sdwa v121, v121 dst_sel:DWORD dst_unused:UNUSED_PAD src0_sel:WORD_1
	v_cvt_f32_f16_e32 v128, v129
	v_cvt_f32_f16_sdwa v129, v129 dst_sel:DWORD dst_unused:UNUSED_PAD src0_sel:WORD_1
	v_pk_add_f32 v[134:135], v[134:135], v[140:141]
	v_pk_add_f32 v[126:127], v[126:127], v[130:131]
	v_cvt_f32_f16_e32 v130, v124
	v_cvt_f32_f16_sdwa v131, v124 dst_sel:DWORD dst_unused:UNUSED_PAD src0_sel:WORD_1
	v_cvt_f32_f16_e32 v140, v132
	v_cvt_f32_f16_sdwa v141, v132 dst_sel:DWORD dst_unused:UNUSED_PAD src0_sel:WORD_1
	v_pk_add_f32 v[120:121], v[120:121], v[128:129]
	v_cvt_f32_f16_e32 v124, v125
	v_cvt_f32_f16_sdwa v125, v125 dst_sel:DWORD dst_unused:UNUSED_PAD src0_sel:WORD_1
	v_cvt_f32_f16_e32 v128, v133
	v_cvt_f32_f16_sdwa v129, v133 dst_sel:DWORD dst_unused:UNUSED_PAD src0_sel:WORD_1
	v_pk_add_f32 v[130:131], v[130:131], v[140:141]
	v_pk_add_f32 v[14:15], v[14:15], v[134:135]
	v_pk_add_f32 v[118:119], v[118:119], v[122:123]
	v_pk_add_f32 v[124:125], v[124:125], v[128:129]
	v_pk_add_f32 v[126:127], v[126:127], v[130:131]
	v_pk_add_f32 v[120:121], v[120:121], v[124:125]
	ds_bpermute_b32 v134, v139, v14
	ds_bpermute_b32 v135, v139, v15
	ds_bpermute_b32 v122, v139, v118
	ds_bpermute_b32 v123, v139, v119
	ds_bpermute_b32 v130, v139, v126
	ds_bpermute_b32 v131, v139, v127
	ds_bpermute_b32 v124, v139, v120
	ds_bpermute_b32 v125, v139, v121
	s_waitcnt lgkmcnt(6)
	v_pk_add_f32 v[14:15], v[14:15], v[134:135]
	s_waitcnt lgkmcnt(4)
	v_pk_add_f32 v[118:119], v[118:119], v[122:123]
	s_waitcnt lgkmcnt(2)
	v_pk_add_f32 v[126:127], v[126:127], v[130:131]
	ds_bpermute_b32 v134, v138, v14
	s_waitcnt lgkmcnt(1)
	v_pk_add_f32 v[120:121], v[120:121], v[124:125]
	ds_bpermute_b32 v135, v138, v15
	ds_bpermute_b32 v122, v138, v118
	ds_bpermute_b32 v123, v138, v119
	ds_bpermute_b32 v130, v138, v126
	ds_bpermute_b32 v131, v138, v127
	ds_bpermute_b32 v124, v138, v120
	ds_bpermute_b32 v125, v138, v121
	s_waitcnt lgkmcnt(6)
	v_pk_add_f32 v[14:15], v[14:15], v[134:135]
	s_waitcnt lgkmcnt(4)
	v_pk_add_f32 v[118:119], v[118:119], v[122:123]
	s_waitcnt lgkmcnt(2)
	v_pk_add_f32 v[126:127], v[126:127], v[130:131]
	ds_bpermute_b32 v134, v137, v14
	s_waitcnt lgkmcnt(1)
	v_pk_add_f32 v[120:121], v[120:121], v[124:125]
	ds_bpermute_b32 v135, v137, v15
	ds_bpermute_b32 v122, v137, v118
	ds_bpermute_b32 v123, v137, v119
	ds_bpermute_b32 v130, v137, v126
	ds_bpermute_b32 v131, v137, v127
	ds_bpermute_b32 v124, v137, v120
	ds_bpermute_b32 v125, v137, v121
	v_cmp_gt_u32_e32 vcc, 8, v238
	s_and_saveexec_b64 s[8:9], vcc
	s_cbranch_execz .LBB0_423
	s_waitcnt lgkmcnt(6)
	v_pk_add_f32 v[132:133], v[14:15], v[134:135]
	s_waitcnt lgkmcnt(4)
	v_pk_add_f32 v[134:135], v[118:119], v[122:123]
	s_waitcnt lgkmcnt(2)
	v_pk_add_f32 v[118:119], v[126:127], v[130:131]
	s_waitcnt lgkmcnt(0)
	v_pk_add_f32 v[120:121], v[120:121], v[124:125]
	ds_write_b128 v136, v[132:135]
	ds_write_b128 v136, v[118:121] offset:16

; template<int THRL> __device__ __forceinline__ void attn_unit(int b,int h,int qb,const bf16*Q,const bf16*__restrict__ K,const bf16*__restrict__ V,bf16*O,char*shm,const float*KMg,const float*rel_bias,bool newhead,bf16x8 (&qr)[4],const bf16*Qnext){
;     ...
;       asm volatile("s_waitcnt vmcnt(0) lgkmcnt(0)\n\ts_barrier":::"memory");
;       float t_=0.f;
;       #pragma unroll
;       for(int w8=0;w8<8;++w8)t_+=kpart[w8*512+tid];
;       kml[tid]=t_*(1.0f/256.0f); }
;     for(int e=tid;e<4*NBT;e+=NW*64){ const int cpy=e/NBT,i=e%NBT,j=i+cpy; float v=-INFINITY;
;       const int dist=(NBT-1-j)-256;
;       if(j<NBT&&dist>=0){ int bk=dist; if(dist>=16){ bk=16+(int)(logf((float)dist/16.0f)/logf(8.0f)*16.0f); bk=bk<31?bk:31; } v=(rel_bias[bk*NHEAD+h]-rel_bias[31*NHEAD+h])*1.4426950408889634f; }
;       btl[e]=v; }
.LBB0_437:
	s_or_b64 exec, exec, s[8:9]
	v_lshl_add_u32 v4, v17, 2, 0
	s_waitcnt vmcnt(0) lgkmcnt(0)
	s_barrier
	v_add_u32_e32 v5, 0x1b800, v4
	ds_read2st64_b32 v[2:3], v5 offset1:8
	s_movk_i32 s5, 0xa00
	v_cmp_gt_i32_e32 vcc, s5, v17
	s_waitcnt lgkmcnt(0)
	v_add_f32_e32 v2, 0, v2
	v_add_f32_e32 v6, v2, v3
	ds_read2st64_b32 v[2:3], v5 offset0:16 offset1:24
	s_waitcnt lgkmcnt(0)
	v_add_f32_e32 v2, v6, v2
	v_add_f32_e32 v6, v2, v3
	ds_read2st64_b32 v[2:3], v5 offset0:32 offset1:40
	s_waitcnt lgkmcnt(0)
	v_add_f32_e32 v2, v6, v2
	v_add_f32_e32 v6, v2, v3
	ds_read2st64_b32 v[2:3], v5 offset0:48 offset1:56
	s_waitcnt lgkmcnt(0)
	v_add_f32_e32 v2, v6, v2
	v_add_f32_e32 v2, v2, v3
	v_mul_f32_e32 v2, 0x3b800000, v2
	v_add_u32_e32 v3, 0x14800, v4
	ds_write_b32 v3, v2
	s_cmp_lt_u32 s43, 0x800
	s_cselect_b64 s[22:23], -1, 0
	s_and_b64 vcc, vcc, s[22:23]
	s_and_saveexec_b64 s[8:9], vcc
	s_cbranch_execz .LBB0_444
	v_readlane_b32 s80, v253, 4
	s_lshl_b32 s5, s76, 2
	v_readlane_b32 s82, v253, 6
	v_readlane_b32 s83, v253, 7
	s_add_u32 s16, s82, s5
	v_readlane_b32 s5, v255, 24
	s_addc_u32 s17, s83, 0
	v_sub_u32_e32 v2, 0x17f, v17
	v_lshl_add_u32 v3, v17, 2, s5
	s_mov_b64 s[22:23], 0
	v_mov_b32_e32 v4, v17
	v_readlane_b32 s81, v253, 5
	v_readlane_b32 s84, v253, 8
	v_readlane_b32 s85, v253, 9
	v_readlane_b32 s86, v253, 10
	v_readlane_b32 s87, v253, 11
	v_readlane_b32 s88, v253, 12
	v_readlane_b32 s89, v253, 13
	v_readlane_b32 s90, v253, 14
	v_readlane_b32 s91, v253, 15
	v_readlane_b32 s92, v253, 16
	v_readlane_b32 s93, v253, 17
	v_readlane_b32 s94, v253, 18
	v_readlane_b32 s95, v253, 19
	s_branch .LBB0_441
